# natten bias: 40 serialized exec-masked LDS reads batched into unconditional reads + cndmask; MLA S-phase K-fragment prefetch
# speedup vs baseline: 1.0402x; 1.0105x over previous
.LBB0_347:
	s_bitcmp1_b32 s85, 0
	s_cselect_b32 s3, 0x2c00, 0
	s_cmp_gt_i32 s85, s97
	s_mov_b64 s[86:87], -1
	s_cbranch_scc1 .LBB0_435
	v_add_u32_e32 v2, s85, v195
	v_cmp_ge_u32_e32 vcc, v2, v194
	v_cmp_lt_u32_e64 s[86:87], v2, v214
	v_mov_b64_e32 v[50:51], v[114:115]
	v_mov_b64_e32 v[34:35], v[98:99]
	v_mov_b64_e32 v[18:19], v[82:83]
	v_mov_b64_e32 v[2:3], v[66:67]
	s_and_b64 vcc, vcc, s[86:87]
	v_mov_b32_e32 v221, v163
	v_mov_b32_e32 v166, v0
	v_mov_b32_e32 v222, v220
	v_mov_b32_e32 v162, v219
	v_mov_b64_e32 v[52:53], v[116:117]
	v_mov_b64_e32 v[54:55], v[118:119]
	v_mov_b64_e32 v[56:57], v[120:121]
	v_mov_b64_e32 v[58:59], v[122:123]
	v_mov_b64_e32 v[60:61], v[124:125]
	v_mov_b64_e32 v[62:63], v[126:127]
	v_mov_b64_e32 v[64:65], v[128:129]
	v_mov_b64_e32 v[36:37], v[100:101]
	v_mov_b64_e32 v[38:39], v[102:103]
	v_mov_b64_e32 v[40:41], v[104:105]
	v_mov_b64_e32 v[42:43], v[106:107]
	v_mov_b64_e32 v[44:45], v[108:109]
	v_mov_b64_e32 v[46:47], v[110:111]
	v_mov_b64_e32 v[48:49], v[112:113]
	v_mov_b64_e32 v[20:21], v[84:85]
	v_mov_b64_e32 v[22:23], v[86:87]
	v_mov_b64_e32 v[24:25], v[88:89]
	v_mov_b64_e32 v[26:27], v[90:91]
	v_mov_b64_e32 v[28:29], v[92:93]
	v_mov_b64_e32 v[30:31], v[94:95]
	v_mov_b64_e32 v[32:33], v[96:97]
	v_mov_b64_e32 v[4:5], v[68:69]
	v_mov_b64_e32 v[6:7], v[70:71]
	v_mov_b64_e32 v[8:9], v[72:73]
	v_mov_b64_e32 v[10:11], v[74:75]
	v_mov_b64_e32 v[12:13], v[76:77]
	v_mov_b64_e32 v[14:15], v[78:79]
	v_mov_b64_e32 v[16:17], v[80:81]
	s_and_saveexec_b64 s[86:87], vcc
	s_cbranch_execz .LBB0_434
	v_lshl_add_u32 v162, s3, 1, v215
	ds_read_b128 v[2:5], v162
	ds_read_b128 v[22:25], v162 offset:32
	ds_read_b128 v[54:57], v192 offset:47104
	ds_read_b128 v[58:61], v192 offset:47136
	s_waitcnt lgkmcnt(3)
	v_mfma_f32_32x32x16_bf16 v[38:53], v[2:5], v[130:133], 0
	s_waitcnt lgkmcnt(1)
	v_mfma_f32_32x32x16_bf16 v[6:21], v[2:5], v[54:57], 0
	ds_read_b128 v[2:5], v162 offset:64
	ds_read_b128 v[62:65], v192 offset:47168
	v_mfma_f32_32x32x16_bf16 v[38:53], v[22:25], v[134:137], v[38:53]
	s_waitcnt lgkmcnt(2)
	v_mfma_f32_32x32x16_bf16 v[6:21], v[22:25], v[58:61], v[6:21]
	s_waitcnt lgkmcnt(1)
	v_mfma_f32_32x32x16_bf16 v[38:53], v[2:5], v[138:141], v[38:53]
	s_waitcnt lgkmcnt(0)
	v_mfma_f32_32x32x16_bf16 v[6:21], v[2:5], v[62:65], v[6:21]
	ds_read_b128 v[2:5], v162 offset:96
	ds_read_b128 v[164:167], v192 offset:47200
	s_waitcnt lgkmcnt(1)
	v_mfma_f32_32x32x16_bf16 v[38:53], v[2:5], v[142:145], v[38:53]
	s_waitcnt lgkmcnt(0)
	v_mfma_f32_32x32x16_bf16 v[6:21], v[2:5], v[164:167], v[6:21]
	ds_read_b128 v[2:5], v162 offset:4608
	s_waitcnt lgkmcnt(0)
	v_mfma_f32_32x32x16_bf16 v[22:37], v[2:5], v[130:133], 0
	v_mfma_f32_32x32x16_bf16 v[2:17], v[2:5], v[54:57], 0
	ds_read_b128 v[54:57], v162 offset:4640
	s_waitcnt lgkmcnt(0)
	v_mfma_f32_32x32x16_bf16 v[22:37], v[54:57], v[134:137], v[22:37]
	v_mfma_f32_32x32x16_bf16 v[2:17], v[54:57], v[58:61], v[2:17]
	ds_read_b128 v[54:57], v162 offset:4672
	s_waitcnt lgkmcnt(0)
	v_mfma_f32_32x32x16_bf16 v[22:37], v[54:57], v[138:141], v[22:37]
	v_mfma_f32_32x32x16_bf16 v[2:17], v[54:57], v[62:65], v[2:17]
	ds_read_b128 v[54:57], v162 offset:4704
	s_waitcnt lgkmcnt(0)
	v_mfma_f32_32x32x16_bf16 v[22:37], v[54:57], v[142:145], v[22:37]
	v_mfma_f32_32x32x16_bf16 v[2:17], v[54:57], v[164:167], v[2:17]
	s_nop 10
	v_mov_b32_e32 v35, 0xff800000
	ds_read_b32 v27, v218 offset:32
	ds_read_b32 v26, v218 offset:36
	ds_read_b32 v29, v218 offset:40
	ds_read_b32 v28, v218 offset:44
	ds_read_b32 v31, v218 offset:64
	ds_read_b32 v30, v218 offset:68
	ds_read_b32 v33, v218 offset:72
	ds_read_b32 v32, v218 offset:76
	ds_read_b32 v164, v218 offset:96
	ds_read_b32 v162, v218 offset:100
	ds_read_b32 v177, v218 offset:104
	ds_read_b32 v178, v218 offset:108
	ds_read_b32 v179, v218 offset:128
	ds_read_b32 v166, v218 offset:132
	ds_read_b32 v181, v218 offset:136
	ds_read_b32 v182, v218 offset:140
	ds_read_b32 v183, v218 offset:160
	ds_read_b32 v184, v218 offset:164
	ds_read_b32 v185, v218 offset:168
	ds_read_b32 v34, v218 offset:172
	s_waitcnt lgkmcnt(10)
	v_add_f32_e32 v27, v38, v27
	v_add_f32_e32 v26, v39, v26
	v_add_f32_e32 v29, v40, v29
	v_add_f32_e32 v28, v41, v28
	v_add_f32_e32 v31, v42, v31
	v_add_f32_e32 v30, v43, v30
	v_add_f32_e32 v33, v44, v33
	v_add_f32_e32 v32, v45, v32
	v_add_f32_e32 v164, v46, v164
	v_add_f32_e32 v162, v47, v162
	s_waitcnt lgkmcnt(0)
	v_add_f32_e32 v177, v48, v177
	v_add_f32_e32 v178, v49, v178
	v_add_f32_e32 v179, v50, v179
	v_add_f32_e32 v166, v51, v166
	v_add_f32_e32 v181, v52, v181
	v_add_f32_e32 v182, v53, v182
	v_add_f32_e32 v183, v22, v183
	v_add_f32_e32 v184, v23, v184
	v_add_f32_e32 v185, v24, v185
	v_add_f32_e32 v23, v25, v34
	v_cndmask_b32_e64 v27, v35, v27, s[0:1]
	v_cndmask_b32_e64 v26, v35, v26, s[4:5]
	v_cndmask_b32_e64 v29, v35, v29, s[6:7]
	v_cndmask_b32_e64 v28, v35, v28, s[8:9]
	v_cndmask_b32_e64 v31, v35, v31, s[10:11]
	v_cndmask_b32_e64 v30, v35, v30, s[12:13]
	v_cndmask_b32_e64 v33, v35, v33, s[14:15]
	v_cndmask_b32_e64 v32, v35, v32, s[16:17]
	v_cndmask_b32_e64 v164, v35, v164, s[18:19]
	v_cndmask_b32_e64 v162, v35, v162, s[20:21]
	v_cndmask_b32_e64 v177, v35, v177, s[22:23]
	v_cndmask_b32_e64 v178, v35, v178, s[24:25]
	v_cndmask_b32_e64 v179, v35, v179, s[26:27]
	v_cndmask_b32_e64 v166, v35, v166, s[28:29]
	v_cndmask_b32_e64 v181, v35, v181, s[30:31]
	v_cndmask_b32_e64 v182, v35, v182, s[34:35]
	v_cndmask_b32_e64 v183, v35, v183, s[36:37]
	v_cndmask_b32_e64 v184, v35, v184, s[38:39]
	v_cndmask_b32_e64 v185, v35, v185, s[40:41]
	v_cndmask_b32_e64 v23, v35, v23, s[42:43]
	v_and_b32_e32 v24, 64, v200
	v_xor_b32_e32 v22, 32, v200
	v_add_u32_e32 v24, 64, v24
	v_cmp_lt_i32_e32 vcc, v22, v24
	s_nop 1
	v_cndmask_b32_e32 v22, v200, v22, vcc
	v_lshlrev_b32_e32 v22, 2, v22
	v_max3_f32 v24, v27, v26, v29
	v_max3_f32 v24, v24, v28, v31
	v_max3_f32 v24, v24, v30, v33
	v_max3_f32 v24, v24, v32, v164
	v_max3_f32 v24, v24, v162, v177
	v_max3_f32 v24, v24, v178, v179
	v_max3_f32 v24, v24, v166, v181
	v_max3_f32 v24, v24, v182, v183
	v_max3_f32 v24, v24, v184, v185
	s_mov_b32 s88, 0xff800000
	v_max3_f32 v24, v24, v23, s88
	ds_bpermute_b32 v25, v22, v24
	v_mov_b64_e32 v[34:35], v[98:99]
	v_mov_b64_e32 v[50:51], v[114:115]
	v_mov_b64_e32 v[36:37], v[100:101]
	v_mov_b64_e32 v[38:39], v[102:103]
	s_waitcnt lgkmcnt(0)
	v_max_f32_e32 v25, v25, v25
	v_max_f32_e32 v24, v24, v25
	v_cmp_gt_f32_e32 vcc, v24, v163
	v_mov_b64_e32 v[40:41], v[104:105]
	v_mov_b64_e32 v[42:43], v[106:107]
	v_mov_b64_e32 v[44:45], v[108:109]
	v_mov_b64_e32 v[46:47], v[110:111]
	v_mov_b64_e32 v[48:49], v[112:113]
	v_mov_b64_e32 v[52:53], v[116:117]
	v_mov_b64_e32 v[54:55], v[118:119]
	v_mov_b64_e32 v[56:57], v[120:121]
	v_mov_b64_e32 v[58:59], v[122:123]
	v_mov_b64_e32 v[60:61], v[124:125]
	v_mov_b64_e32 v[62:63], v[126:127]
	v_mov_b64_e32 v[64:65], v[128:129]
	v_mov_b32_e32 v165, v220
	v_mov_b32_e32 v221, v163
	s_cbranch_vccz .LBB0_391
	v_max_f32_e32 v24, v24, v24
	v_max_f32_e32 v25, v163, v163
	v_max_f32_e32 v221, v25, v24
	v_sub_f32_e32 v24, v163, v221
	v_exp_f32_e32 v24, v24
	s_nop 0
	v_mul_f32_e32 v165, v220, v24
	v_pk_mul_f32 v[64:65], v[128:129], v[24:25] op_sel_hi:[1,0]
	v_pk_mul_f32 v[62:63], v[126:127], v[24:25] op_sel_hi:[1,0]
	v_pk_mul_f32 v[60:61], v[124:125], v[24:25] op_sel_hi:[1,0]
	v_pk_mul_f32 v[58:59], v[122:123], v[24:25] op_sel_hi:[1,0]
	v_pk_mul_f32 v[56:57], v[120:121], v[24:25] op_sel_hi:[1,0]
	v_pk_mul_f32 v[54:55], v[118:119], v[24:25] op_sel_hi:[1,0]
	v_pk_mul_f32 v[52:53], v[116:117], v[24:25] op_sel_hi:[1,0]
	v_pk_mul_f32 v[50:51], v[114:115], v[24:25] op_sel_hi:[1,0]
	v_pk_mul_f32 v[48:49], v[112:113], v[24:25] op_sel_hi:[1,0]
	v_pk_mul_f32 v[46:47], v[110:111], v[24:25] op_sel_hi:[1,0]
	v_pk_mul_f32 v[44:45], v[108:109], v[24:25] op_sel_hi:[1,0]
	v_pk_mul_f32 v[42:43], v[106:107], v[24:25] op_sel_hi:[1,0]
	v_pk_mul_f32 v[40:41], v[104:105], v[24:25] op_sel_hi:[1,0]
	v_pk_mul_f32 v[38:39], v[102:103], v[24:25] op_sel_hi:[1,0]
	v_pk_mul_f32 v[36:37], v[100:101], v[24:25] op_sel_hi:[1,0]
	v_pk_mul_f32 v[34:35], v[98:99], v[24:25] op_sel_hi:[1,0]
.LBB0_391:
	v_sub_f32_e32 v24, v27, v221
	v_exp_f32_e32 v167, v24
	v_sub_f32_e32 v24, v26, v221
	v_exp_f32_e32 v168, v24
	v_sub_f32_e32 v24, v29, v221
	v_exp_f32_e32 v169, v24
	v_sub_f32_e32 v24, v28, v221
	v_exp_f32_e32 v170, v24
	v_sub_f32_e32 v24, v31, v221
	v_exp_f32_e32 v171, v24
	v_sub_f32_e32 v24, v30, v221
	v_exp_f32_e32 v172, v24
	v_sub_f32_e32 v24, v33, v221
	v_exp_f32_e32 v173, v24
	v_sub_f32_e32 v24, v32, v221
	v_exp_f32_e32 v174, v24
	v_sub_f32_e32 v24, v164, v221
	v_exp_f32_e32 v175, v24
	v_sub_f32_e32 v24, v162, v221
	v_lshl_add_u32 v180, s3, 1, v216
	v_exp_f32_e32 v176, v24
	v_sub_f32_e32 v24, v177, v221
	v_exp_f32_e32 v177, v24
	v_sub_f32_e32 v24, v178, v221
	v_add_u32_e32 v162, 0x3000, v180
	v_exp_f32_e32 v178, v24
	ds_read2_b64 v[24:27], v162 offset0:128 offset1:130
	v_sub_f32_e32 v28, v179, v221
	v_exp_f32_e32 v179, v28
	v_cvt_pk_bf16_f32 v28, v167, v168
	v_cvt_pk_bf16_f32 v29, v169, v170
	v_cvt_pk_bf16_f32 v30, v171, v172
	v_cvt_pk_bf16_f32 v31, v173, v174
	v_add_u32_e32 v164, 0x4000, v180
	ds_read2_b64 v[186:189], v164 offset0:192 offset1:194
	s_waitcnt lgkmcnt(1)
	v_mfma_f32_32x32x16_bf16 v[50:65], v[24:27], v[28:31], v[50:65]
	v_sub_f32_e32 v24, v166, v221
	v_exp_f32_e32 v180, v24
	v_sub_f32_e32 v24, v181, v221
	v_exp_f32_e32 v181, v24
	v_sub_f32_e32 v24, v182, v221
	v_exp_f32_e32 v182, v24
	ds_read2_b64 v[24:27], v162 offset0:132 offset1:134
	s_waitcnt lgkmcnt(1)
	v_mfma_f32_32x32x16_bf16 v[34:49], v[186:189], v[28:31], v[34:49]
	v_sub_f32_e32 v28, v183, v221
	v_exp_f32_e32 v183, v28
	v_cvt_pk_bf16_f32 v28, v175, v176
	v_cvt_pk_bf16_f32 v29, v177, v178
	v_cvt_pk_bf16_f32 v30, v179, v180
	v_cvt_pk_bf16_f32 v31, v181, v182
	ds_read2_b64 v[222:225], v164 offset0:196 offset1:198
	v_sub_f32_e32 v23, v23, v221
	s_waitcnt lgkmcnt(1)
	v_mfma_f32_32x32x16_bf16 v[50:65], v[24:27], v[28:31], v[50:65]
	v_sub_f32_e32 v24, v184, v221
	v_exp_f32_e32 v184, v24
	v_sub_f32_e32 v24, v185, v221
	v_exp_f32_e32 v185, v24
	ds_read2_b64 v[24:27], v162 offset0:136 offset1:138
	v_exp_f32_e32 v186, v23
	v_sub_f32_e32 v23, 0xff800000, v221
	v_exp_f32_e32 v187, v23
	s_waitcnt lgkmcnt(1)
	v_mfma_f32_32x32x16_bf16 v[34:49], v[222:225], v[28:31], v[34:49]
	v_cvt_pk_bf16_f32 v28, v183, v184
	v_cvt_pk_bf16_f32 v29, v185, v186
	v_cvt_pk_bf16_f32 v30, v187, v187
	v_mov_b32_e32 v31, v30
	v_mov_b32_e32 v188, 0xff800000
	s_waitcnt lgkmcnt(0)
	v_mfma_f32_32x32x16_bf16 v[50:65], v[24:27], v[28:31], v[50:65]
	ds_read2_b64 v[24:27], v164 offset0:200 offset1:202
	s_waitcnt lgkmcnt(0)
	v_mfma_f32_32x32x16_bf16 v[34:49], v[24:27], v[28:31], v[34:49]
	ds_read2_b64 v[24:27], v162 offset0:140 offset1:142
	v_mov_b32_e32 v28, v30
	v_mov_b32_e32 v29, v30
	s_waitcnt lgkmcnt(0)
	s_nop 0
	v_mfma_f32_32x32x16_bf16 v[50:65], v[24:27], v[28:31], v[50:65]
	ds_read2_b64 v[24:27], v164 offset0:204 offset1:206
	s_waitcnt lgkmcnt(0)
	v_mfma_f32_32x32x16_bf16 v[34:49], v[24:27], v[28:31], v[34:49]
	v_mov_b32_e32 v23, 0xff800000
	ds_read_b32 v189, v218
	ds_read_b32 v188, v218 offset:4
	ds_read_b32 v209, v218 offset:8
	ds_read_b32 v208, v218 offset:12
	ds_read_b32 v225, v218 offset:32
	ds_read_b32 v223, v218 offset:36
	ds_read_b32 v233, v218 offset:40
	ds_read_b32 v231, v218 offset:44
	ds_read_b32 v237, v218 offset:64
	ds_read_b32 v212, v218 offset:68
	ds_read_b32 v227, v218 offset:72
	ds_read_b32 v224, v218 offset:76
	ds_read_b32 v235, v218 offset:96
	ds_read_b32 v229, v218 offset:100
	ds_read_b32 v234, v218 offset:104
	ds_read_b32 v226, v218 offset:108
	ds_read_b32 v230, v218 offset:128
	ds_read_b32 v228, v218 offset:132
	ds_read_b32 v236, v218 offset:136
	ds_read_b32 v232, v218 offset:140
	s_waitcnt lgkmcnt(10)
	v_add_f32_e32 v189, v18, v189
	v_add_f32_e32 v188, v19, v188
	v_add_f32_e32 v209, v20, v209
	v_add_f32_e32 v208, v21, v208
	v_add_f32_e32 v225, v2, v225
	v_add_f32_e32 v223, v3, v223
	v_add_f32_e32 v233, v4, v233
	v_add_f32_e32 v231, v5, v231
	v_add_f32_e32 v237, v6, v237
	v_add_f32_e32 v212, v7, v212
	s_waitcnt lgkmcnt(0)
	v_add_f32_e32 v227, v8, v227
	v_add_f32_e32 v224, v9, v224
	v_add_f32_e32 v235, v10, v235
	v_add_f32_e32 v229, v11, v229
	v_add_f32_e32 v234, v12, v234
	v_add_f32_e32 v226, v13, v226
	v_add_f32_e32 v230, v14, v230
	v_add_f32_e32 v228, v15, v228
	v_add_f32_e32 v236, v16, v236
	v_add_f32_e32 v232, v17, v232
	v_cndmask_b32_e64 v189, v23, v189, s[44:45]
	v_cndmask_b32_e64 v188, v23, v188, s[46:47]
	v_cndmask_b32_e64 v209, v23, v209, s[48:49]
	v_cndmask_b32_e64 v208, v23, v208, s[50:51]
	v_cndmask_b32_e64 v225, v23, v225, s[52:53]
	v_cndmask_b32_e64 v223, v23, v223, s[54:55]
	v_cndmask_b32_e64 v233, v23, v233, s[56:57]
	v_cndmask_b32_e64 v231, v23, v231, s[58:59]
	v_cndmask_b32_e64 v237, v23, v237, s[60:61]
	v_cndmask_b32_e64 v212, v23, v212, s[62:63]
	v_cndmask_b32_e64 v227, v23, v227, s[64:65]
	v_cndmask_b32_e64 v224, v23, v224, s[66:67]
	v_cndmask_b32_e64 v235, v23, v235, s[68:69]
	v_cndmask_b32_e64 v229, v23, v229, s[70:71]
	v_cndmask_b32_e64 v234, v23, v234, s[72:73]
	v_cndmask_b32_e64 v226, v23, v226, s[74:75]
	v_cndmask_b32_e64 v230, v23, v230, s[76:77]
	v_cndmask_b32_e64 v228, v23, v228, s[78:79]
	v_cndmask_b32_e64 v236, v23, v236, s[80:81]
	v_cndmask_b32_e64 v232, v23, v232, s[82:83]
	v_max3_f32 v2, v189, s88, v188
	v_max3_f32 v2, v2, v209, v208
	v_max3_f32 v2, v2, v225, v223
	v_max3_f32 v2, v2, v233, v231
	v_max3_f32 v2, v2, v237, v212
	v_max3_f32 v2, v2, v227, v224
	v_max3_f32 v2, v2, v235, v229
	v_max3_f32 v2, v2, v234, v226
	v_max3_f32 v2, v2, v230, v228
	v_max3_f32 v2, v2, v236, v232
	ds_bpermute_b32 v3, v22, v2
	v_mov_b64_e32 v[18:19], v[82:83]
	v_mov_b64_e32 v[20:21], v[84:85]
	v_mov_b64_e32 v[22:23], v[86:87]
	v_mov_b64_e32 v[24:25], v[88:89]
	s_waitcnt lgkmcnt(0)
	v_max_f32_e32 v3, v3, v3
	v_max_f32_e32 v222, v2, v3
	v_mov_b64_e32 v[2:3], v[66:67]
	v_cmp_gt_f32_e32 vcc, v222, v0
	v_mov_b64_e32 v[4:5], v[68:69]
	v_mov_b64_e32 v[6:7], v[70:71]
	v_mov_b64_e32 v[8:9], v[72:73]
	v_mov_b64_e32 v[10:11], v[74:75]
	v_mov_b64_e32 v[12:13], v[76:77]
	v_mov_b64_e32 v[14:15], v[78:79]
	v_mov_b64_e32 v[16:17], v[80:81]
	v_mov_b64_e32 v[26:27], v[90:91]
	v_mov_b64_e32 v[28:29], v[92:93]
	v_mov_b64_e32 v[30:31], v[94:95]
	v_mov_b64_e32 v[32:33], v[96:97]
	v_mov_b32_e32 v238, v219
	v_mov_b32_e32 v166, v0
	s_cbranch_vccz .LBB0_433
	v_max_f32_e32 v2, v222, v222
	v_max_f32_e32 v3, v0, v0
	v_max_f32_e32 v166, v3, v2
	v_sub_f32_e32 v2, v0, v166
	v_exp_f32_e32 v2, v2
	s_nop 0
	v_mul_f32_e32 v238, v219, v2
	v_pk_mul_f32 v[32:33], v[96:97], v[2:3] op_sel_hi:[1,0]
	v_pk_mul_f32 v[30:31], v[94:95], v[2:3] op_sel_hi:[1,0]
	v_pk_mul_f32 v[28:29], v[92:93], v[2:3] op_sel_hi:[1,0]
	v_pk_mul_f32 v[26:27], v[90:91], v[2:3] op_sel_hi:[1,0]
	v_pk_mul_f32 v[24:25], v[88:89], v[2:3] op_sel_hi:[1,0]
	v_pk_mul_f32 v[22:23], v[86:87], v[2:3] op_sel_hi:[1,0]
	v_pk_mul_f32 v[20:21], v[84:85], v[2:3] op_sel_hi:[1,0]
	v_pk_mul_f32 v[18:19], v[82:83], v[2:3] op_sel_hi:[1,0]
	v_pk_mul_f32 v[16:17], v[80:81], v[2:3] op_sel_hi:[1,0]
	v_pk_mul_f32 v[14:15], v[78:79], v[2:3] op_sel_hi:[1,0]
	v_pk_mul_f32 v[12:13], v[76:77], v[2:3] op_sel_hi:[1,0]
	v_pk_mul_f32 v[10:11], v[74:75], v[2:3] op_sel_hi:[1,0]
	v_pk_mul_f32 v[8:9], v[72:73], v[2:3] op_sel_hi:[1,0]
	v_pk_mul_f32 v[6:7], v[70:71], v[2:3] op_sel_hi:[1,0]
	v_pk_mul_f32 v[4:5], v[68:69], v[2:3] op_sel_hi:[1,0]
	v_pk_mul_f32 v[2:3], v[66:67], v[2:3] op_sel_hi:[1,0]

.LBB0_746:
	s_bitcmp1_b32 s11, 0
	s_cselect_b32 s12, 0x2c00, 0
	s_lshl_b32 s13, s12, 1
	v_add3_u32 v15, v192, s13, v191
	ds_read_b128 v[2:5], v15
	ds_read_b128 v[10:13], v194 offset:47104
	ds_read_b128 v[240:243], v15 offset:32
	ds_read_b128 v[216:219], v194 offset:47136
	ds_read_b128 v[244:247], v15 offset:64
	ds_read_b128 v[6:9], v194 offset:47168
	ds_read_b128 v[248:251], v15 offset:96
	ds_read_b128 v[220:223], v194 offset:47200
	s_waitcnt lgkmcnt(7)
	v_mfma_f32_32x32x16_bf16 v[112:127], v[2:5], v[144:147], 0
	s_waitcnt lgkmcnt(6)
	v_mfma_f32_32x32x16_bf16 v[96:111], v[2:5], v[10:13], 0
	ds_read_b128 v[2:5], v15 offset:128
	ds_read_b128 v[224:227], v194 offset:47232
	s_waitcnt lgkmcnt(7)
	v_mfma_f32_32x32x16_bf16 v[112:127], v[240:243], v[148:151], v[112:127]
	s_waitcnt lgkmcnt(6)
	v_mfma_f32_32x32x16_bf16 v[96:111], v[240:243], v[216:219], v[96:111]
	ds_read_b128 v[240:243], v15 offset:160
	ds_read_b128 v[228:231], v194 offset:47264
	s_waitcnt lgkmcnt(7)
	v_mfma_f32_32x32x16_bf16 v[112:127], v[244:247], v[152:155], v[112:127]
	s_waitcnt lgkmcnt(6)
	v_mfma_f32_32x32x16_bf16 v[96:111], v[244:247], v[6:9], v[96:111]
	ds_read_b128 v[244:247], v15 offset:6656
	s_waitcnt lgkmcnt(6)
	v_mfma_f32_32x32x16_bf16 v[112:127], v[248:251], v[156:159], v[112:127]
	s_waitcnt lgkmcnt(5)
	v_mfma_f32_32x32x16_bf16 v[96:111], v[248:251], v[220:223], v[96:111]
	ds_read_b128 v[248:251], v15 offset:6688
	s_waitcnt lgkmcnt(5)
	v_mfma_f32_32x32x16_bf16 v[112:127], v[2:5], v[160:163], v[112:127]
	s_waitcnt lgkmcnt(4)
	v_mfma_f32_32x32x16_bf16 v[96:111], v[2:5], v[224:227], v[96:111]
	ds_read_b128 v[2:5], v15 offset:6720
	s_waitcnt lgkmcnt(4)
	v_mfma_f32_32x32x16_bf16 v[112:127], v[240:243], v[164:167], v[112:127]
	s_waitcnt lgkmcnt(3)
	v_mfma_f32_32x32x16_bf16 v[96:111], v[240:243], v[228:231], v[96:111]
	ds_read_b128 v[240:243], v15 offset:6752
	s_waitcnt lgkmcnt(3)
	v_mfma_f32_32x32x16_bf16 v[128:143], v[244:247], v[144:147], 0
	v_mfma_f32_32x32x16_bf16 v[80:95], v[244:247], v[10:13], 0
	ds_read_b128 v[244:247], v15 offset:6784
	s_waitcnt lgkmcnt(3)
	v_mfma_f32_32x32x16_bf16 v[128:143], v[248:251], v[148:151], v[128:143]
	v_mfma_f32_32x32x16_bf16 v[80:95], v[248:251], v[216:219], v[80:95]
	ds_read_b128 v[248:251], v15 offset:6816
	s_waitcnt lgkmcnt(3)
	v_mfma_f32_32x32x16_bf16 v[128:143], v[2:5], v[152:155], v[128:143]
	v_mfma_f32_32x32x16_bf16 v[80:95], v[2:5], v[6:9], v[80:95]
	s_waitcnt lgkmcnt(2)
	v_mfma_f32_32x32x16_bf16 v[128:143], v[240:243], v[156:159], v[128:143]
	v_mfma_f32_32x32x16_bf16 v[80:95], v[240:243], v[220:223], v[80:95]
	s_waitcnt lgkmcnt(1)
	v_mfma_f32_32x32x16_bf16 v[128:143], v[244:247], v[160:163], v[128:143]
	v_mfma_f32_32x32x16_bf16 v[80:95], v[244:247], v[224:227], v[80:95]
	s_waitcnt lgkmcnt(0)
	v_mfma_f32_32x32x16_bf16 v[128:143], v[248:251], v[164:167], v[128:143]
	v_mfma_f32_32x32x16_bf16 v[80:95], v[248:251], v[228:231], v[80:95]
	v_max_f32_e32 v2, v113, v113
	v_max_f32_e32 v3, v112, v112
	v_max_f32_e32 v2, v3, v2
	v_max3_f32 v2, v2, v114, v115
	v_max3_f32 v2, v2, v116, v117
	v_max3_f32 v2, v2, v118, v119
	v_max3_f32 v2, v2, v120, v121
	v_max3_f32 v2, v2, v122, v123
	v_max3_f32 v2, v2, v124, v125
	v_max3_f32 v2, v2, v126, v127
	s_nop 0
	v_max3_f32 v2, v2, v128, v129
	v_max3_f32 v2, v2, v130, v131
	v_max3_f32 v2, v2, v132, v133
	v_max3_f32 v2, v2, v134, v135
	v_max3_f32 v2, v2, v136, v137
	v_max3_f32 v2, v2, v138, v139
	v_max3_f32 v2, v2, v140, v141
	v_max3_f32 v2, v2, v142, v143
	ds_bpermute_b32 v3, v189, v2
	s_waitcnt lgkmcnt(0)
	v_max_f32_e32 v3, v3, v3
	v_max_f32_e32 v2, v2, v3
	v_cmp_gt_f32_e32 vcc, v2, v215
	s_cbranch_vccz .LBB0_748
	v_max_f32_e32 v2, v2, v2
	v_max_f32_e32 v3, v215, v215
	v_max_f32_e32 v3, v3, v2
	v_sub_f32_e32 v2, v215, v3
	v_exp_f32_e32 v2, v2
	v_mov_b32_e32 v215, v3
	v_mul_f32_e32 v0, v0, v2
	v_pk_mul_f32 v[78:79], v[78:79], v[2:3] op_sel_hi:[1,0]
	v_pk_mul_f32 v[76:77], v[76:77], v[2:3] op_sel_hi:[1,0]
	v_pk_mul_f32 v[74:75], v[74:75], v[2:3] op_sel_hi:[1,0]
	v_pk_mul_f32 v[72:73], v[72:73], v[2:3] op_sel_hi:[1,0]
	v_pk_mul_f32 v[70:71], v[70:71], v[2:3] op_sel_hi:[1,0]
	v_pk_mul_f32 v[68:69], v[68:69], v[2:3] op_sel_hi:[1,0]
	v_pk_mul_f32 v[66:67], v[66:67], v[2:3] op_sel_hi:[1,0]
	v_pk_mul_f32 v[64:65], v[64:65], v[2:3] op_sel_hi:[1,0]
	v_pk_mul_f32 v[62:63], v[62:63], v[2:3] op_sel_hi:[1,0]
	v_pk_mul_f32 v[60:61], v[60:61], v[2:3] op_sel_hi:[1,0]
	v_pk_mul_f32 v[58:59], v[58:59], v[2:3] op_sel_hi:[1,0]
	v_pk_mul_f32 v[56:57], v[56:57], v[2:3] op_sel_hi:[1,0]
	v_pk_mul_f32 v[54:55], v[54:55], v[2:3] op_sel_hi:[1,0]
	v_pk_mul_f32 v[52:53], v[52:53], v[2:3] op_sel_hi:[1,0]
	v_pk_mul_f32 v[50:51], v[50:51], v[2:3] op_sel_hi:[1,0]
	v_pk_mul_f32 v[48:49], v[48:49], v[2:3] op_sel_hi:[1,0]
